# RWKV pass-0 token loop re-mapped to 8 keys x 1 column per thread (3-level reductions, 36 instead of 48 VALU ops per token); pass-1 keeps the deferred o-reduction
# speedup vs baseline: 1.0102x; 1.0038x over previous
; template <int pass>
; __device__ __forceinline__ void rw_item(const Params& p, int l, int seg, int h, LAS float* sm, int tid, int lane, int wave) {
;     ...
;     if (pass == 0) {
;         float* ql = Lm + ((size_t)(seg * 6 + h) * 64 + j0) * 64 + kq * 4;
;         *(f32x4*)ql = (f32x4){sA[0].x, sA[0].y, sA[1].x, sA[1].y}; *(f32x4*)(ql + 64) = (f32x4){sB[0].x, sB[0].y, sB[1].x, sB[1].y};
;         float* qp = Pm + ((size_t)(seg * 6 + h) * 64 + j0) * 64 + kq * 4;
;         *(f32x4*)qp = (f32x4){pA[0].x, pA[0].y, pA[1].x, pA[1].y}; *(f32x4*)(qp + 64) = (f32x4){pB[0].x, pB[0].y, pB[1].x, pB[1].y};
;     }
.LBB0_521:
	v_and_b32_e32 v250, 7, v30
	v_lshrrev_b32_e32 v251, 3, v30
	s_lshl_b32 s8, s18, 14
	v_lshlrev_b32_e32 v250, 5, v250
	v_lshl_add_u32 v250, v251, 8, v250
	v_add_u32_e32 v250, s8, v250
	v_add_u32_e32 v251, 0xfb80000, v250
	v_add_u32_e32 v250, 0xef80000, v250
	s_waitcnt lgkmcnt(0)
	global_store_dwordx4 v250, v[188:191], s[92:93]
	global_store_dwordx4 v250, v[192:195], s[92:93] offset:16
	global_store_dwordx4 v251, v[196:199], s[92:93]
	global_store_dwordx4 v251, v[200:203], s[92:93] offset:16

;     __device__ __forceinline__ const float* in(int i) const { return (const float*)(const __attribute__((address_space(1))) float*)ld(i); }
; __device__ __forceinline__ void lds_barrier() { asm volatile("s_waitcnt lgkmcnt(0)" ::: "memory"); __builtin_amdgcn_s_barrier(); asm volatile("" ::: "memory"); }
; #define RW_LOAD(sb) do { _Pragma("unroll") for (int e = 0; e < 2; ++e) { const size_t g = gbase + (size_t)((sb) * TS + trow + 8 * e) * RWW; \
;         rw_[e] = Ww[g]; rk_[e] = Kk[g]; ra_[e] = Al[g]; rb_[e] = Be[g]; rv_[e] = Vv[g]; if (pass == 1) rq_[e] = Rr[g]; } } while (0)
; #define RW_STORE(buf) do { _Pragma("unroll") for (int e = 0; e < 2; ++e) { LAS float* b_ = sm + (buf) * 6144 + tid + 512 * e; \
;         b_[1024] = rw_[e]; b_[2048] = bf2f(rk_[e]); b_[3072] = bf2f(ra_[e]); b_[4096] = bf2f(rb_[e]); b_[5120] = bf2f(rv_[e]); if (pass == 1) b_[0] = bf2f(rq_[e]); } } while (0)
; template <int pass>
; __device__ __forceinline__ void rw_item(const Params& p, int l, int seg, int h, LAS float* sm, int tid, int lane, int wave) {
;     ...
;     const int kq = tid & 15, jp = tid >> 4, j0 = 2 * jp, j1 = 2 * jp + 1;
;     f32x2 sA[2], sB[2], pA[2], pB[2];
; #pragma unroll
;     for (int i = 0; i < 2; ++i) {
;         sA[i] = (f32x2){0.f, 0.f}; sB[i] = (f32x2){0.f, 0.f};
;         pA[i] = (f32x2){(kq * 4 + 2 * i == j0) ? 1.f : 0.f, (kq * 4 + 2 * i + 1 == j0) ? 1.f : 0.f};
;         pB[i] = (f32x2){(kq * 4 + 2 * i == j1) ? 1.f : 0.f, (kq * 4 + 2 * i + 1 == j1) ? 1.f : 0.f};
;     }
;     if (pass == 1 && seg > 0) {
;         const float* q = Lm + ((size_t)((seg - 1) * 6 + h) * 64 + j0) * 64 + kq * 4;
;         const f32x4 a = *(const f32x4*)q, b = *(const f32x4*)(q + 64);
;         sA[0] = a.xy; sA[1] = a.zw; sB[0] = b.xy; sB[1] = b.zw;
;     }
;     float lnw = 0.f, lnb = 0.f;
;     if (pass == 1) { lnw = p.in(17)[l * RWW + h * 64 + lane]; lnb = p.in(18)[l * RWW + h * 64 + lane]; }
;     float rw_[2]; bf16_t rk_[2], ra_[2], rb_[2], rv_[2], rq_[2];
;     const size_t gbase = (size_t)(seg * SEG) * RWW + h * 64 + (tid & 63);
;     const int trow = tid >> 6;
;     ...
;     lds_barrier();
;     RW_LOAD(0); RW_STORE(0); RW_LOAD(1);
;     lds_barrier();
.LBB0_723:
	s_mul_hi_i32 s0, s18, 0x2aaaaaab
	s_lshr_b32 s1, s0, 31
	s_add_i32 s19, s0, s1
	s_mul_i32 s0, s19, 6
	s_sub_i32 s22, s18, s0
	s_waitcnt lgkmcnt(0)
	v_readfirstlane_b32 s0, v32
	v_readfirstlane_b32 s1, v33
	s_add_u32 s8, s0, 0x13780000
	s_addc_u32 s9, s1, 0
	s_add_u32 s10, s0, 0x14f80000
	s_addc_u32 s11, s1, 0
	s_add_u32 s12, s0, 0x12b80000
	s_addc_u32 s13, s1, 0
	s_add_u32 s14, s0, 0x14380000
	s_addc_u32 s15, s1, 0
	s_add_u32 s20, s0, 0x16780000
	s_addc_u32 s21, s1, 0
	s_lshl_b32 s22, s22, 6
	s_lshl_b32 s23, s19, 7
	s_mul_i32 s19, s19, 0xc000
	s_ashr_i32 s24, s22, 31
	s_mul_hi_i32 s23, s23, 0x180
	s_add_u32 s19, s19, s22
	s_addc_u32 s22, s23, s24
	s_waitcnt vmcnt(0)
	v_ashrrev_i32_e32 v18, 6, v30
	v_or_b32_e32 v24, s19, v46
	v_mov_b32_e32 v25, s22
	v_add_u32_e32 v0, 8, v18
	v_mad_i64_i32 v[2:3], s[22:23], v18, s60, v[24:25]
	v_mad_i64_i32 v[10:11], s[22:23], v0, s60, v[24:25]
	s_waitcnt lgkmcnt(0)
	s_barrier
	v_lshl_add_u64 v[4:5], v[2:3], 2, s[20:21]
	v_lshlrev_b64 v[2:3], 1, v[2:3]
	v_lshl_add_u64 v[12:13], v[10:11], 2, s[20:21]
	v_lshlrev_b64 v[10:11], 1, v[10:11]
	global_load_dword v19, v[4:5], off
	global_load_dword v20, v[12:13], off
	v_lshl_add_u64 v[4:5], s[12:13], 0, v[2:3]
	v_lshl_add_u64 v[6:7], s[10:11], 0, v[2:3]
	v_lshl_add_u64 v[8:9], s[14:15], 0, v[2:3]
	v_lshl_add_u64 v[2:3], s[8:9], 0, v[2:3]
	v_lshl_add_u64 v[12:13], s[12:13], 0, v[10:11]
	v_lshl_add_u64 v[14:15], s[10:11], 0, v[10:11]
	v_lshl_add_u64 v[16:17], s[14:15], 0, v[10:11]
	v_lshl_add_u64 v[10:11], s[8:9], 0, v[10:11]
	v_add_u32_e32 v0, 16, v18
	global_load_ushort v21, v[4:5], off
	global_load_ushort v22, v[6:7], off
	global_load_ushort v23, v[8:9], off
	global_load_ushort v28, v[2:3], off
	s_nop 0
	global_load_ushort v12, v[12:13], off
	s_nop 0
	global_load_ushort v13, v[14:15], off
	s_nop 0
	global_load_ushort v14, v[16:17], off
	s_nop 0
	global_load_ushort v10, v[10:11], off
	v_mad_i64_i32 v[2:3], s[22:23], v0, s60, v[24:25]
	v_lshlrev_b64 v[4:5], 1, v[2:3]
	v_lshl_add_u64 v[6:7], s[12:13], 0, v[4:5]
	global_load_ushort v11, v[6:7], off
	v_lshl_add_u64 v[6:7], s[10:11], 0, v[4:5]
	global_load_ushort v15, v[6:7], off
	v_lshl_add_u64 v[6:7], s[14:15], 0, v[4:5]
	v_lshl_add_u64 v[4:5], s[8:9], 0, v[4:5]
	v_add_u32_e32 v0, 24, v18
	v_lshl_add_u64 v[2:3], v[2:3], 2, s[20:21]
	global_load_ushort v17, v[4:5], off
	global_load_dword v27, v[2:3], off
	v_mad_i64_i32 v[4:5], s[22:23], v0, s60, v[24:25]
	v_lshl_add_u64 v[2:3], v[4:5], 2, s[20:21]
	global_load_ushort v16, v[6:7], off
	global_load_dword v43, v[2:3], off
	v_lshlrev_b64 v[6:7], 1, v[4:5]
	v_lshl_add_u64 v[8:9], s[12:13], 0, v[6:7]
	global_load_ushort v29, v[8:9], off
	v_lshl_add_u64 v[8:9], s[10:11], 0, v[6:7]
	global_load_ushort v32, v[8:9], off
	v_lshl_add_u64 v[8:9], s[14:15], 0, v[6:7]
	global_load_ushort v8, v[8:9], off
	v_lshl_add_u64 v[6:7], s[8:9], 0, v[6:7]
	global_load_ushort v6, v[6:7], off
	v_lshlrev_b32_e32 v0, 2, v30
	v_ashrrev_i32_e32 v9, 3, v30
	v_add_u32_e32 v42, 0, v0
	v_and_b32_e32 v26, -2, v9
	v_and_b32_e32 v31, 60, v0
	v_cmp_eq_u32_e32 vcc, v31, v26
	v_or_b32_e32 v2, 2, v31
	v_readlane_b32 s2, v254, 4
	v_cndmask_b32_e64 v0, 0, 1.0, vcc
	v_cmp_eq_u32_e32 vcc, v2, v26
	v_mov_b32_e32 v3, v1
	v_add_u32_e32 v45, 32, v18
	v_cndmask_b32_e64 v2, 0, 1.0, vcc
	s_mov_b32 s19, 0
	s_mov_b64 s[22:23], 0
	s_waitcnt vmcnt(18)
	ds_write2st64_b32 v42, v19, v20 offset0:16 offset1:24
	s_waitcnt vmcnt(17)
	v_lshlrev_b32_e32 v4, 16, v21
	s_waitcnt vmcnt(16)
	v_lshlrev_b32_e32 v5, 16, v22
	s_waitcnt vmcnt(15)
	v_lshlrev_b32_e32 v7, 16, v23
	s_waitcnt vmcnt(14)
	v_lshlrev_b32_e32 v19, 16, v28
	s_waitcnt vmcnt(13)
	v_lshlrev_b32_e32 v12, 16, v12
	s_waitcnt vmcnt(12)
	v_lshlrev_b32_e32 v13, 16, v13
	ds_write2st64_b32 v42, v4, v12 offset0:32 offset1:40
	ds_write2st64_b32 v42, v5, v13 offset0:48 offset1:56
	s_waitcnt vmcnt(11)
	v_lshlrev_b32_e32 v4, 16, v14
	ds_write2st64_b32 v42, v7, v4 offset0:64 offset1:72
	s_waitcnt vmcnt(10)
	v_lshlrev_b32_e32 v4, 16, v10
	ds_write2st64_b32 v42, v19, v4 offset0:80 offset1:88
	s_waitcnt lgkmcnt(0)
	s_barrier
	v_mov_b32_e32 v14, v1
	v_mov_b32_e32 v12, v1
	v_mov_b32_e32 v13, v1
	v_mov_b32_e32 v4, v1
	v_mov_b32_e32 v5, v0
	v_mov_b32_e32 v7, v2
	s_waitcnt vmcnt(3)
	v_perm_b32 v44, v29, v11, s47
	s_waitcnt vmcnt(2)
	v_perm_b32 v48, v32, v15, s47
	v_mov_b32_e32 v15, v1
	s_waitcnt vmcnt(1)
	v_perm_b32 v49, v8, v16, s47
	v_lshlrev_b32_e32 v8, 2, v9
	v_and_b32_e32 v8, -8, v8
	v_add_u32_e32 v46, s2, v8
	v_and_b32_e32 v8, 15, v30
	v_readlane_b32 s2, v254, 6
	s_waitcnt vmcnt(0)
	v_perm_b32 v50, v6, v17, s47
	v_lshrrev_b32_e32 v246, 16, v44
	v_lshrrev_b32_e32 v247, 16, v48
	v_lshrrev_b32_e32 v248, 16, v49
	v_lshrrev_b32_e32 v249, 16, v50
	v_mov_b64_e32 v[18:19], v[14:15]
	v_lshl_add_u32 v47, v8, 4, s2
	v_mov_b64_e32 v[10:11], v[2:3]
	v_mov_b32_e32 v6, v1
	v_mov_b64_e32 v[16:17], v[12:13]
	v_mov_b64_e32 v[8:9], v[0:1]
	v_and_b32_e32 v250, 7, v30
	v_lshrrev_b32_e32 v251, 3, v30
	v_lshlrev_b32_e32 v250, 3, v250
	v_sub_u32_e32 v250, v251, v250
	v_mov_b32_e32 v188, v1
	v_mov_b32_e32 v189, v1
	v_mov_b32_e32 v190, v1
	v_mov_b32_e32 v191, v1
	v_mov_b32_e32 v192, v1
	v_mov_b32_e32 v193, v1
	v_mov_b32_e32 v194, v1
	v_mov_b32_e32 v195, v1
	v_cmp_eq_u32_e32 vcc, 0, v250
	s_nop 1
	v_cndmask_b32_e64 v196, 0, 1.0, vcc
	v_cmp_eq_u32_e32 vcc, 1, v250
	s_nop 1
	v_cndmask_b32_e64 v197, 0, 1.0, vcc
	v_cmp_eq_u32_e32 vcc, 2, v250
	s_nop 1
	v_cndmask_b32_e64 v198, 0, 1.0, vcc
	v_cmp_eq_u32_e32 vcc, 3, v250
	s_nop 1
	v_cndmask_b32_e64 v199, 0, 1.0, vcc
	v_cmp_eq_u32_e32 vcc, 4, v250
	s_nop 1
	v_cndmask_b32_e64 v200, 0, 1.0, vcc
	v_cmp_eq_u32_e32 vcc, 5, v250
	s_nop 1
	v_cndmask_b32_e64 v201, 0, 1.0, vcc
	v_cmp_eq_u32_e32 vcc, 6, v250
	s_nop 1
	v_cndmask_b32_e64 v202, 0, 1.0, vcc
	v_cmp_eq_u32_e32 vcc, 7, v250
	s_nop 1
	v_cndmask_b32_e64 v203, 0, 1.0, vcc
	s_branch .LBB0_725

; #define LAS __attribute__((address_space(3)))
; template <int pass>
; __device__ __forceinline__ void rw_item(const Params& p, int l, int seg, int h, LAS float* sm, int tid, int lane, int wave) {
;     ...
;         const int cur = sb & 1;
;         const LAS float* bf = sm + cur * 6144;
;         LAS float* ob = sm + 12288 + cur * 1024;
;         float pf_rk[2] = {0.f, 0.f}; bf16_t pf_v[2] = {0, 0}, pf_g[2] = {0, 0};
;         if (pass == 1) {
; #pragma unroll
;             for (int rr = 0; rr < 2; ++rr) { const int tok = seg * SEG + sb * TS + wave + 8 * rr; const size_t g = (size_t)tok * RWW + h * 64 + lane; pf_rk[rr] = RK[(size_t)tok * 8 + h]; pf_v[rr] = Vv[g]; pf_g[rr] = Gg[g]; }
;         }
;         f32x4 nw4 = *(const LAS f32x4*)(bf + 1024 + kq * 4), nk4 = *(const LAS f32x4*)(bf + 2048 + kq * 4);
;         f32x4 na4 = *(const LAS f32x4*)(bf + 3072 + kq * 4), nb4 = *(const LAS f32x4*)(bf + 4096 + kq * 4);
;         f32x2 nvv = *(const LAS f32x2*)(bf + 5120 + j0);
;         f32x4 nq4 = (pass == 1) ? *(const LAS f32x4*)(bf + kq * 4) : (f32x4){0.f, 0.f, 0.f, 0.f};
.LBB0_725:
	s_and_b32 s24, s19, 1
	s_mul_i32 s25, s24, 0x6000
	v_and_b32_e32 v250, 7, v30
	v_lshrrev_b32_e32 v251, 3, v30
	v_lshl_add_u32 v250, v250, 5, s25
	v_lshl_add_u32 v251, v251, 2, s25
	ds_read_b128 v[204:207], v250 offset:16384
	ds_read_b128 v[208:211], v250 offset:16400
	ds_read_b128 v[212:215], v250 offset:12288
	ds_read_b128 v[216:219], v250 offset:12304
	ds_read_b128 v[220:223], v250 offset:8192
	ds_read_b128 v[224:227], v250 offset:8208
	ds_read_b128 v[228:231], v250 offset:4096
	ds_read_b128 v[232:235], v250 offset:4112
	ds_read_b32 v236, v251 offset:20480
	s_mov_b32 s31, 0
; template <int pass>
; __device__ __forceinline__ void rw_item(const Params& p, int l, int seg, int h, LAS float* sm, int tid, int lane, int wave) {
;     ...
; #pragma unroll 8
;         for (int t = 0; t < TS; ++t) {
;             const f32x4 w4 = nw4, k4 = nk4, a4 = na4, b4 = nb4, q4 = nq4; const f32x2 vv = nvv;
;             {
;                 const int tn = (t + 1 < TS) ? t + 1 : t, on = tn * 64 + kq * 4;
;                 nw4 = *(const LAS f32x4*)(bf + 1024 + on); nk4 = *(const LAS f32x4*)(bf + 2048 + on);
;                 na4 = *(const LAS f32x4*)(bf + 3072 + on); nb4 = *(const LAS f32x4*)(bf + 4096 + on);
;                 nvv = *(const LAS f32x2*)(bf + 5120 + tn * 64 + j0);
;                 if (pass == 1) nq4 = *(const LAS f32x4*)(bf + on);
;             }
;             const f32x2 vA = {vv.x, vv.x}, vB = {vv.y, vv.y};
;             f32x2 ua = b4.xy * sA[0], ub = b4.xy * sB[0];
;             ua = b4.zw * sA[1] + ua; ub = b4.zw * sB[1] + ub;
;             float uA = ua.x + ua.y, uB = ub.x + ub.y, gA = 0.f, gB = 0.f;
;             if (pass == 0) {
;                 f32x2 qa = b4.xy * pA[0], qb = b4.xy * pB[0];
;                 qa = b4.zw * pA[1] + qa; qb = b4.zw * pB[1] + qb;
;                 gA = qa.x + qa.y; gB = qb.x + qb.y;
;                 kq_sum16x4(uA, uB, gA, gB);
;             } else { uA = kq_sum<16>(uA); uB = kq_sum<16>(uB); }
;             const f32x2 uA2 = {uA, uA}, uB2 = {uB, uB};
;             { const f32x2 t0_ = k4.xy * vA - a4.xy * uA2, t1_ = k4.zw * vA - a4.zw * uA2; sA[0] = w4.xy * sA[0] + t0_; sA[1] = w4.zw * sA[1] + t1_; }
;             { const f32x2 t0_ = k4.xy * vB - a4.xy * uB2, t1_ = k4.zw * vB - a4.zw * uB2; sB[0] = w4.xy * sB[0] + t0_; sB[1] = w4.zw * sB[1] + t1_; }
;             if (pass == 0) {
;                 const f32x2 gA2 = {gA, gA}, gB2 = {gB, gB};
;                 pA[0] = w4.xy * pA[0] - a4.xy * gA2; pA[1] = w4.zw * pA[1] - a4.zw * gA2;
;                 pB[0] = w4.xy * pB[0] - a4.xy * gB2; pB[1] = w4.zw * pB[1] - a4.zw * gB2;
;             } else {
;                 f32x2 oa = q4.xy * sA[0], ob2 = q4.xy * sB[0];
;                 oa = q4.zw * sA[1] + oa; ob2 = q4.zw * sB[1] + ob2;
;                 const float oA = kq_sum<16>(oa.x + oa.y), oB = kq_sum<16>(ob2.x + ob2.y);
;                 if (kq == 0) *(LAS f32x2*)(ob + t * 64 + j0) = (f32x2){oA, oB};
;             }
;         }
.LBB0_726:
	s_waitcnt lgkmcnt(0)
	ds_read_b128 v[2:5], v250 offset:16640
	ds_read_b128 v[6:9], v250 offset:16656
	ds_read_b128 v[10:13], v250 offset:12544
	ds_read_b128 v[14:17], v250 offset:12560
	ds_read_b128 v[18:21], v250 offset:8448
	ds_read_b128 v[32:35], v250 offset:8464
	ds_read_b128 v[36:39], v250 offset:4352
	ds_read_b128 v[52:55], v250 offset:4368
	ds_read_b32 v28, v251 offset:20736
	v_pk_mul_f32 v[238:239], v[204:205], v[188:189]
	v_pk_mul_f32 v[240:241], v[204:205], v[196:197]
	v_pk_fma_f32 v[238:239], v[206:207], v[190:191], v[238:239]
	v_pk_fma_f32 v[240:241], v[206:207], v[198:199], v[240:241]
	v_pk_fma_f32 v[238:239], v[208:209], v[192:193], v[238:239]
	v_pk_fma_f32 v[240:241], v[208:209], v[200:201], v[240:241]
	v_pk_fma_f32 v[238:239], v[210:211], v[194:195], v[238:239]
	v_pk_fma_f32 v[240:241], v[210:211], v[202:203], v[240:241]
	v_add_f32_e32 v238, v238, v239
	v_add_f32_e32 v240, v240, v241
	v_pk_mul_f32 v[220:221], v[220:221], v[236:237] op_sel_hi:[1,0]
	v_pk_mul_f32 v[222:223], v[222:223], v[236:237] op_sel_hi:[1,0]
	v_add_f32_dpp v238, v238, v238 quad_perm:[1,0,3,2] row_mask:0xf bank_mask:0xf bound_ctrl:1
	v_add_f32_dpp v240, v240, v240 quad_perm:[1,0,3,2] row_mask:0xf bank_mask:0xf bound_ctrl:1
	v_pk_mul_f32 v[224:225], v[224:225], v[236:237] op_sel_hi:[1,0]
	v_pk_mul_f32 v[226:227], v[226:227], v[236:237] op_sel_hi:[1,0]
	v_add_f32_dpp v238, v238, v238 quad_perm:[2,3,0,1] row_mask:0xf bank_mask:0xf bound_ctrl:1
	v_add_f32_dpp v240, v240, v240 quad_perm:[2,3,0,1] row_mask:0xf bank_mask:0xf bound_ctrl:1
	v_pk_mul_f32 v[196:197], v[228:229], v[196:197]
	v_pk_mul_f32 v[198:199], v[230:231], v[198:199]
	v_add_f32_dpp v238, v238, v238 row_half_mirror row_mask:0xf bank_mask:0xf bound_ctrl:1
	v_add_f32_dpp v240, v240, v240 row_half_mirror row_mask:0xf bank_mask:0xf bound_ctrl:1
	v_pk_mul_f32 v[200:201], v[232:233], v[200:201]
	v_pk_mul_f32 v[202:203], v[234:235], v[202:203]
	v_pk_fma_f32 v[220:221], v[212:213], v[238:239], v[220:221] op_sel_hi:[1,0,1] neg_lo:[1,0,0] neg_hi:[1,0,0]
	v_pk_fma_f32 v[222:223], v[214:215], v[238:239], v[222:223] op_sel_hi:[1,0,1] neg_lo:[1,0,0] neg_hi:[1,0,0]
	v_pk_fma_f32 v[224:225], v[216:217], v[238:239], v[224:225] op_sel_hi:[1,0,1] neg_lo:[1,0,0] neg_hi:[1,0,0]
	v_pk_fma_f32 v[226:227], v[218:219], v[238:239], v[226:227] op_sel_hi:[1,0,1] neg_lo:[1,0,0] neg_hi:[1,0,0]
	v_pk_fma_f32 v[188:189], v[228:229], v[188:189], v[220:221]
	v_pk_fma_f32 v[190:191], v[230:231], v[190:191], v[222:223]
	v_pk_fma_f32 v[192:193], v[232:233], v[192:193], v[224:225]
	v_pk_fma_f32 v[194:195], v[234:235], v[194:195], v[226:227]
	v_pk_fma_f32 v[196:197], v[212:213], v[240:241], v[196:197] op_sel_hi:[1,0,1] neg_lo:[1,0,0] neg_hi:[1,0,0]
	v_pk_fma_f32 v[198:199], v[214:215], v[240:241], v[198:199] op_sel_hi:[1,0,1] neg_lo:[1,0,0] neg_hi:[1,0,0]
	v_pk_fma_f32 v[200:201], v[216:217], v[240:241], v[200:201] op_sel_hi:[1,0,1] neg_lo:[1,0,0] neg_hi:[1,0,0]
	v_pk_fma_f32 v[202:203], v[218:219], v[240:241], v[202:203] op_sel_hi:[1,0,1] neg_lo:[1,0,0] neg_hi:[1,0,0]
	v_add_u32_e32 v250, 0x200, v250
	v_add_u32_e32 v251, 0x200, v251
	s_waitcnt lgkmcnt(0)
	ds_read_b128 v[204:207], v250 offset:16384
	ds_read_b128 v[208:211], v250 offset:16400
	ds_read_b128 v[212:215], v250 offset:12288
	ds_read_b128 v[216:219], v250 offset:12304
	ds_read_b128 v[220:223], v250 offset:8192
	ds_read_b128 v[224:227], v250 offset:8208
	ds_read_b128 v[228:231], v250 offset:4096
	ds_read_b128 v[232:235], v250 offset:4112
	ds_read_b32 v236, v251 offset:20480
	v_pk_mul_f32 v[238:239], v[2:3], v[188:189]
	v_pk_mul_f32 v[240:241], v[2:3], v[196:197]
	v_pk_fma_f32 v[238:239], v[4:5], v[190:191], v[238:239]
	v_pk_fma_f32 v[240:241], v[4:5], v[198:199], v[240:241]
	v_pk_fma_f32 v[238:239], v[6:7], v[192:193], v[238:239]
	v_pk_fma_f32 v[240:241], v[6:7], v[200:201], v[240:241]
	v_pk_fma_f32 v[238:239], v[8:9], v[194:195], v[238:239]
	v_pk_fma_f32 v[240:241], v[8:9], v[202:203], v[240:241]
	v_add_f32_e32 v238, v238, v239
	v_add_f32_e32 v240, v240, v241
	v_pk_mul_f32 v[18:19], v[18:19], v[28:29] op_sel_hi:[1,0]
	v_pk_mul_f32 v[20:21], v[20:21], v[28:29] op_sel_hi:[1,0]
	v_add_f32_dpp v238, v238, v238 quad_perm:[1,0,3,2] row_mask:0xf bank_mask:0xf bound_ctrl:1
	v_add_f32_dpp v240, v240, v240 quad_perm:[1,0,3,2] row_mask:0xf bank_mask:0xf bound_ctrl:1
	v_pk_mul_f32 v[32:33], v[32:33], v[28:29] op_sel_hi:[1,0]
	v_pk_mul_f32 v[34:35], v[34:35], v[28:29] op_sel_hi:[1,0]
	v_add_f32_dpp v238, v238, v238 quad_perm:[2,3,0,1] row_mask:0xf bank_mask:0xf bound_ctrl:1
	v_add_f32_dpp v240, v240, v240 quad_perm:[2,3,0,1] row_mask:0xf bank_mask:0xf bound_ctrl:1
	v_pk_mul_f32 v[196:197], v[36:37], v[196:197]
	v_pk_mul_f32 v[198:199], v[38:39], v[198:199]
	v_add_f32_dpp v238, v238, v238 row_half_mirror row_mask:0xf bank_mask:0xf bound_ctrl:1
	v_add_f32_dpp v240, v240, v240 row_half_mirror row_mask:0xf bank_mask:0xf bound_ctrl:1
	v_pk_mul_f32 v[200:201], v[52:53], v[200:201]
	v_pk_mul_f32 v[202:203], v[54:55], v[202:203]
	v_pk_fma_f32 v[18:19], v[10:11], v[238:239], v[18:19] op_sel_hi:[1,0,1] neg_lo:[1,0,0] neg_hi:[1,0,0]
	v_pk_fma_f32 v[20:21], v[12:13], v[238:239], v[20:21] op_sel_hi:[1,0,1] neg_lo:[1,0,0] neg_hi:[1,0,0]
	v_pk_fma_f32 v[32:33], v[14:15], v[238:239], v[32:33] op_sel_hi:[1,0,1] neg_lo:[1,0,0] neg_hi:[1,0,0]
	v_pk_fma_f32 v[34:35], v[16:17], v[238:239], v[34:35] op_sel_hi:[1,0,1] neg_lo:[1,0,0] neg_hi:[1,0,0]
	v_pk_fma_f32 v[188:189], v[36:37], v[188:189], v[18:19]
	v_pk_fma_f32 v[190:191], v[38:39], v[190:191], v[20:21]
	v_pk_fma_f32 v[192:193], v[52:53], v[192:193], v[32:33]
	v_pk_fma_f32 v[194:195], v[54:55], v[194:195], v[34:35]
	v_pk_fma_f32 v[196:197], v[10:11], v[240:241], v[196:197] op_sel_hi:[1,0,1] neg_lo:[1,0,0] neg_hi:[1,0,0]
	v_pk_fma_f32 v[198:199], v[12:13], v[240:241], v[198:199] op_sel_hi:[1,0,1] neg_lo:[1,0,0] neg_hi:[1,0,0]
	v_pk_fma_f32 v[200:201], v[14:15], v[240:241], v[200:201] op_sel_hi:[1,0,1] neg_lo:[1,0,0] neg_hi:[1,0,0]
	v_pk_fma_f32 v[202:203], v[16:17], v[240:241], v[202:203] op_sel_hi:[1,0,1] neg_lo:[1,0,0] neg_hi:[1,0,0]
	s_add_i32 s31, s31, 1
	s_cmp_lg_u32 s31, 8
	s_cbranch_scc1 .LBB0_726
	s_cmp_eq_u32 s19, 7
	s_cbranch_scc1 .LBB0_729
	s_xor_b32 s24, s24, 1
	s_mulk_i32 s24, 0x6000
	s_waitcnt vmcnt(0)
	v_add_u32_e32 v0, s24, v42
	v_lshlrev_b32_e32 v2, 16, v44
	v_lshlrev_b32_e32 v22, 16, v246
	v_lshlrev_b32_e32 v3, 16, v48
	ds_write2st64_b32 v0, v2, v22 offset0:32 offset1:40
	v_lshlrev_b32_e32 v2, 16, v247
	v_lshlrev_b32_e32 v20, 16, v49
	ds_write2st64_b32 v0, v3, v2 offset0:48 offset1:56
	v_lshlrev_b32_e32 v2, 16, v248
	v_lshlrev_b32_e32 v21, 16, v50
	ds_write2st64_b32 v0, v20, v2 offset0:64 offset1:72
	v_lshlrev_b32_e32 v2, 16, v249
	ds_write2st64_b32 v0, v27, v43 offset0:16 offset1:24
	ds_write2st64_b32 v0, v21, v2 offset0:80 offset1:88
